# GQA and diff loops: next-tile LDS staging moved mid-tile (off the barrier critical path)
# speedup vs baseline: 1.0873x; 1.0091x over previous
.Ldg_ci2:
	s_nop 0
	s_waitcnt lgkmcnt(7)
	v_mfma_f32_32x32x16_bf16 v[66:81], v[114:117], v[82:85], v[220:235]
	s_waitcnt lgkmcnt(6)
	v_mfma_f32_32x32x16_bf16 v[66:81], v[118:121], v[86:89], v[66:81]
	s_waitcnt lgkmcnt(5)
	v_mfma_f32_32x32x16_bf16 v[66:81], v[122:125], v[90:93], v[66:81]
	s_waitcnt lgkmcnt(4)
	v_mfma_f32_32x32x16_bf16 v[66:81], v[126:129], v[94:97], v[66:81]
	s_waitcnt lgkmcnt(3)
	v_mfma_f32_32x32x16_bf16 v[236:251], v[142:145], v[82:85], v[220:235]
	ds_read_b128 v[126:129], v193 offset:16384
	ds_read_b128 v[114:117], v193 offset:20480
	s_waitcnt lgkmcnt(4)
	v_mfma_f32_32x32x16_bf16 v[236:251], v[138:141], v[86:89], v[236:251]
	ds_read_b128 v[122:125], v194 offset:16384
	ds_read_b128 v[118:121], v194 offset:20480
	s_waitcnt lgkmcnt(5)
	v_mfma_f32_32x32x16_bf16 v[236:251], v[134:137], v[90:93], v[236:251]
	s_waitcnt lgkmcnt(4)
	v_mfma_f32_32x32x16_bf16 v[236:251], v[130:133], v[94:97], v[236:251]
	ds_read_b128 v[130:133], v193 offset:24576
	ds_read_b128 v[134:137], v193 offset:28672
	ds_read_b128 v[138:141], v194 offset:24576
	ds_read_b128 v[142:145], v194 offset:28672
	s_mov_b64 s[16:17], s[4:5]
	s_and_b64 vcc, exec, s[16:17]
	s_cbranch_vccnz .Ldg_nb0_2
	ds_read2_b32 v[160:161], v148 offset1:1
	ds_read2_b32 v[162:163], v148 offset0:2 offset1:3
	ds_read2_b32 v[164:165], v148 offset0:8 offset1:9
	ds_read2_b32 v[166:167], v148 offset0:10 offset1:11
	ds_read2_b32 v[168:169], v148 offset0:16 offset1:17
	ds_read2_b32 v[170:171], v148 offset0:18 offset1:19
	ds_read2_b32 v[172:173], v148 offset0:24 offset1:25
	ds_read2_b32 v[174:175], v148 offset0:26 offset1:27
	s_waitcnt lgkmcnt(7)
	v_pk_add_f32 v[66:67], v[66:67], v[160:161]
	s_waitcnt lgkmcnt(6)
	v_pk_add_f32 v[68:69], v[68:69], v[162:163]
	s_waitcnt lgkmcnt(5)
	v_pk_add_f32 v[70:71], v[70:71], v[164:165]
	s_waitcnt lgkmcnt(4)
	v_pk_add_f32 v[72:73], v[72:73], v[166:167]
	s_waitcnt lgkmcnt(3)
	v_pk_add_f32 v[74:75], v[74:75], v[168:169]
	s_waitcnt lgkmcnt(2)
	v_pk_add_f32 v[76:77], v[76:77], v[170:171]
	s_waitcnt lgkmcnt(1)
	v_pk_add_f32 v[78:79], v[78:79], v[172:173]
	s_waitcnt lgkmcnt(0)
	v_pk_add_f32 v[80:81], v[80:81], v[174:175]
	s_nop 0

.Ldg_ci5:
	s_nop 0
	s_waitcnt lgkmcnt(7)
	v_mfma_f32_32x32x16_bf16 v[66:81], v[114:117], v[82:85], v[220:235]
	s_waitcnt lgkmcnt(6)
	v_mfma_f32_32x32x16_bf16 v[66:81], v[118:121], v[86:89], v[66:81]
	s_waitcnt lgkmcnt(5)
	v_mfma_f32_32x32x16_bf16 v[66:81], v[122:125], v[90:93], v[66:81]
	s_waitcnt lgkmcnt(4)
	v_mfma_f32_32x32x16_bf16 v[66:81], v[126:129], v[94:97], v[66:81]
	s_waitcnt lgkmcnt(3)
	v_mfma_f32_32x32x16_bf16 v[236:251], v[142:145], v[82:85], v[220:235]
	ds_read_b128 v[126:129], v193 offset:49152
	ds_read_b128 v[114:117], v193 offset:53248
	s_waitcnt lgkmcnt(4)
	v_mfma_f32_32x32x16_bf16 v[236:251], v[138:141], v[86:89], v[236:251]
	ds_read_b128 v[122:125], v194 offset:49152
	ds_read_b128 v[118:121], v194 offset:53248
	s_waitcnt lgkmcnt(5)
	v_mfma_f32_32x32x16_bf16 v[236:251], v[134:137], v[90:93], v[236:251]
	s_waitcnt lgkmcnt(4)
	v_mfma_f32_32x32x16_bf16 v[236:251], v[130:133], v[94:97], v[236:251]
	ds_read_b128 v[130:133], v193 offset:57344
	ds_read_b128 v[134:137], v193 offset:61440
	ds_read_b128 v[138:141], v194 offset:57344
	ds_read_b128 v[142:145], v194 offset:61440
	s_mov_b64 s[16:17], s[4:5]
	s_and_b64 vcc, exec, s[16:17]
	s_cbranch_vccnz .Ldg_nb0_5
	ds_read2_b32 v[160:161], v148 offset0:64 offset1:65
	ds_read2_b32 v[162:163], v148 offset0:66 offset1:67
	ds_read2_b32 v[164:165], v148 offset0:72 offset1:73
	ds_read2_b32 v[166:167], v148 offset0:74 offset1:75
	ds_read2_b32 v[168:169], v148 offset0:80 offset1:81
	ds_read2_b32 v[170:171], v148 offset0:82 offset1:83
	ds_read2_b32 v[172:173], v148 offset0:88 offset1:89
	ds_read2_b32 v[174:175], v148 offset0:90 offset1:91
	s_waitcnt lgkmcnt(7)
	v_pk_add_f32 v[66:67], v[66:67], v[160:161]
	s_waitcnt lgkmcnt(6)
	v_pk_add_f32 v[68:69], v[68:69], v[162:163]
	s_waitcnt lgkmcnt(5)
	v_pk_add_f32 v[70:71], v[70:71], v[164:165]
	s_waitcnt lgkmcnt(4)
	v_pk_add_f32 v[72:73], v[72:73], v[166:167]
	s_waitcnt lgkmcnt(3)
	v_pk_add_f32 v[74:75], v[74:75], v[168:169]
	s_waitcnt lgkmcnt(2)
	v_pk_add_f32 v[76:77], v[76:77], v[170:171]
	s_waitcnt lgkmcnt(1)
	v_pk_add_f32 v[78:79], v[78:79], v[172:173]
	s_waitcnt lgkmcnt(0)
	v_pk_add_f32 v[80:81], v[80:81], v[174:175]
	s_nop 0

.LBB0_302:
	s_waitcnt vmcnt(1)
	ds_write_b128 v224, v[120:123]
	s_waitcnt vmcnt(0)
	ds_write_b64 v225, v[148:149] offset:8192
	ds_write_b64 v226, v[150:151] offset:8192
	s_waitcnt lgkmcnt(0)
	s_barrier
	s_add_i32 s4, s45, -1
	s_cmp_ge_u32 s4, s41
	s_cbranch_scc1 .Lgq_nold1
	v_lshl_add_u64 v[248:249], v[194:195], 0, v[184:185]
	v_add_co_u32_e32 v248, vcc, 0x16049000, v248
	s_nop 1
	v_addc_co_u32_e32 v249, vcc, 0, v249, vcc
	global_load_dwordx4 v[120:123], v[248:249], off
	v_lshl_add_u64 v[248:249], v[196:197], 0, v[184:185]
	v_add_co_u32_e32 v248, vcc, 0x32800000, v248
	s_nop 1
	v_addc_co_u32_e32 v249, vcc, 0, v249, vcc
	global_load_dwordx4 v[148:151], v[248:249], off offset:128
.Lgq_nold1:
	ds_read_b128 v[96:99], v227
	ds_read_b128 v[100:103], v228
	ds_read_b128 v[104:107], v229
	ds_read_b128 v[108:111], v230
	ds_read_b128 v[198:201], v227 offset:4096
	ds_read_b128 v[202:205], v228 offset:4096
	ds_read_b128 v[206:209], v229 offset:4096
	ds_read_b128 v[210:213], v230 offset:4096
	s_waitcnt lgkmcnt(7)
	v_mfma_f32_32x32x16_bf16 v[80:95], v[96:99], v[112:115], v[152:167]
	s_waitcnt lgkmcnt(6)
	v_mfma_f32_32x32x16_bf16 v[80:95], v[100:103], v[116:119], v[80:95]
	s_waitcnt lgkmcnt(5)
	v_mfma_f32_32x32x16_bf16 v[80:95], v[104:107], v[124:127], v[80:95]
	s_waitcnt lgkmcnt(4)
	v_mfma_f32_32x32x16_bf16 v[80:95], v[108:111], v[128:131], v[80:95]
	v_mfma_f32_32x32x16_bf16 v[64:79], v[96:99], v[132:135], v[168:183]
	v_mfma_f32_32x32x16_bf16 v[64:79], v[100:103], v[136:139], v[64:79]
	v_mfma_f32_32x32x16_bf16 v[64:79], v[104:107], v[140:143], v[64:79]
	v_mfma_f32_32x32x16_bf16 v[64:79], v[108:111], v[144:147], v[64:79]
	ds_read_b128 v[232:235], v227 offset:8192
	ds_read_b128 v[236:239], v227 offset:12288
	ds_read_b128 v[240:243], v228 offset:8192
	ds_read_b128 v[244:247], v228 offset:12288
	s_nop 3
	v_max3_f32 v252, v80, v81, v82
	v_max3_f32 v252, v252, v83, v84
	v_max3_f32 v252, v252, v85, v86
	v_max3_f32 v252, v252, v87, v88
	v_max3_f32 v252, v252, v89, v90
	v_max3_f32 v252, v252, v91, v92
	v_max3_f32 v252, v252, v93, v94
	v_max_f32_e32 v252, v252, v95
	v_max3_f32 v253, v64, v65, v66
	v_max3_f32 v253, v253, v67, v68
	v_max3_f32 v253, v253, v69, v70
	v_max3_f32 v253, v253, v71, v72
	v_max3_f32 v253, v253, v73, v74
	v_max3_f32 v253, v253, v75, v76
	v_max3_f32 v253, v253, v77, v78
	v_max_f32_e32 v253, v253, v79
	v_mov_b32_e32 v248, v252
	s_nop 1
	v_permlane32_swap_b32_e32 v252, v248
	v_max_f32_e32 v252, v252, v248
	v_mov_b32_e32 v231, v252
	v_sub_f32_e32 v80, v80, v252
	v_sub_f32_e32 v81, v81, v252
	v_sub_f32_e32 v82, v82, v252
	v_sub_f32_e32 v83, v83, v252
	v_sub_f32_e32 v84, v84, v252
	v_sub_f32_e32 v85, v85, v252
	v_sub_f32_e32 v86, v86, v252
	v_sub_f32_e32 v87, v87, v252
	v_sub_f32_e32 v88, v88, v252
	v_sub_f32_e32 v89, v89, v252
	v_sub_f32_e32 v90, v90, v252
	v_sub_f32_e32 v91, v91, v252
	v_sub_f32_e32 v92, v92, v252
	v_sub_f32_e32 v93, v93, v252
	v_sub_f32_e32 v94, v94, v252
	v_sub_f32_e32 v95, v95, v252
	v_xor_b32_e32 v152, 0x80000000, v231
	v_mov_b32_e32 v153, v152
	v_mov_b32_e32 v154, v152
	v_mov_b32_e32 v155, v152
	v_mov_b32_e32 v156, v152
	v_mov_b32_e32 v157, v152
	v_mov_b32_e32 v158, v152
	v_mov_b32_e32 v159, v152
	v_mov_b32_e32 v160, v152
	v_mov_b32_e32 v161, v152
	v_mov_b32_e32 v162, v152
	v_mov_b32_e32 v163, v152
	v_mov_b32_e32 v164, v152
	v_mov_b32_e32 v165, v152
	v_mov_b32_e32 v166, v152
	v_mov_b32_e32 v167, v152
	v_mov_b32_e32 v248, v253
	s_nop 1
	v_permlane32_swap_b32_e32 v253, v248
	v_max_f32_e32 v253, v253, v248
	v_mov_b32_e32 v223, v253
	v_sub_f32_e32 v64, v64, v253
	v_sub_f32_e32 v65, v65, v253
	v_sub_f32_e32 v66, v66, v253
	v_sub_f32_e32 v67, v67, v253
	v_sub_f32_e32 v68, v68, v253
	v_sub_f32_e32 v69, v69, v253
	v_sub_f32_e32 v70, v70, v253
	v_sub_f32_e32 v71, v71, v253
	v_sub_f32_e32 v72, v72, v253
	v_sub_f32_e32 v73, v73, v253
	v_sub_f32_e32 v74, v74, v253
	v_sub_f32_e32 v75, v75, v253
	v_sub_f32_e32 v76, v76, v253
	v_sub_f32_e32 v77, v77, v253
	v_sub_f32_e32 v78, v78, v253
	v_sub_f32_e32 v79, v79, v253
	v_xor_b32_e32 v168, 0x80000000, v223
	v_mov_b32_e32 v169, v168
	v_mov_b32_e32 v170, v168
	v_mov_b32_e32 v171, v168
	v_mov_b32_e32 v172, v168
	v_mov_b32_e32 v173, v168
	v_mov_b32_e32 v174, v168
	v_mov_b32_e32 v175, v168
	v_mov_b32_e32 v176, v168
	v_mov_b32_e32 v177, v168
	v_mov_b32_e32 v178, v168
	v_mov_b32_e32 v179, v168
	v_mov_b32_e32 v180, v168
	v_mov_b32_e32 v181, v168
	v_mov_b32_e32 v182, v168
	v_mov_b32_e32 v183, v168
	v_exp_f32_e32 v80, v80
	v_exp_f32_e32 v81, v81
	v_exp_f32_e32 v82, v82
	v_exp_f32_e32 v83, v83
	v_exp_f32_e32 v84, v84
	v_exp_f32_e32 v85, v85
	v_exp_f32_e32 v86, v86
	v_exp_f32_e32 v87, v87
	v_exp_f32_e32 v88, v88
	v_exp_f32_e32 v89, v89
	v_exp_f32_e32 v90, v90
	v_exp_f32_e32 v91, v91
	v_exp_f32_e32 v92, v92
	v_exp_f32_e32 v93, v93
	v_exp_f32_e32 v94, v94
	v_exp_f32_e32 v95, v95
	v_add_f32_e32 v104, v80, v81
	v_add_f32_e32 v105, v82, v83
	v_add_f32_e32 v106, v84, v85
	v_add_f32_e32 v107, v86, v87
	v_add_f32_e32 v108, v88, v89
	v_add_f32_e32 v109, v90, v91
	v_add_f32_e32 v110, v92, v93
	v_add_f32_e32 v111, v94, v95
	v_add_f32_e32 v104, v104, v105
	v_add_f32_e32 v106, v106, v107
	v_add_f32_e32 v108, v108, v109
	v_add_f32_e32 v110, v110, v111
	v_add_f32_e32 v104, v104, v106
	v_add_f32_e32 v108, v108, v110
	v_add_f32_e32 v104, v104, v108
	v_add_f32_e32 v250, v250, v104
	v_cvt_pk_bf16_f32 v96, v80, v81
	v_cvt_pk_bf16_f32 v97, v82, v83
	v_cvt_pk_bf16_f32 v98, v84, v85
	v_cvt_pk_bf16_f32 v99, v86, v87
	v_cvt_pk_bf16_f32 v100, v88, v89
	v_cvt_pk_bf16_f32 v101, v90, v91
	v_cvt_pk_bf16_f32 v102, v92, v93
	v_cvt_pk_bf16_f32 v103, v94, v95
	v_exp_f32_e32 v64, v64
	v_exp_f32_e32 v65, v65
	v_exp_f32_e32 v66, v66
	v_exp_f32_e32 v67, v67
	v_exp_f32_e32 v68, v68
	v_exp_f32_e32 v69, v69
	v_exp_f32_e32 v70, v70
	v_exp_f32_e32 v71, v71
	v_exp_f32_e32 v72, v72
	v_exp_f32_e32 v73, v73
	v_exp_f32_e32 v74, v74
	v_exp_f32_e32 v75, v75
	v_exp_f32_e32 v76, v76
	v_exp_f32_e32 v77, v77
	v_exp_f32_e32 v78, v78
	v_exp_f32_e32 v79, v79
	v_add_f32_e32 v104, v64, v65
	v_add_f32_e32 v105, v66, v67
	v_add_f32_e32 v106, v68, v69
	v_add_f32_e32 v107, v70, v71
	v_add_f32_e32 v108, v72, v73
	v_add_f32_e32 v109, v74, v75
	v_add_f32_e32 v110, v76, v77
	v_add_f32_e32 v111, v78, v79
	v_add_f32_e32 v104, v104, v105
	v_add_f32_e32 v106, v106, v107
	v_add_f32_e32 v108, v108, v109
	v_add_f32_e32 v110, v110, v111
	v_add_f32_e32 v104, v104, v106
	v_add_f32_e32 v108, v108, v110
	v_add_f32_e32 v104, v104, v108
	v_add_f32_e32 v251, v251, v104
	v_cvt_pk_bf16_f32 v104, v64, v65
	v_cvt_pk_bf16_f32 v105, v66, v67
	v_cvt_pk_bf16_f32 v106, v68, v69
	v_cvt_pk_bf16_f32 v107, v70, v71
	v_cvt_pk_bf16_f32 v108, v72, v73
	v_cvt_pk_bf16_f32 v109, v74, v75
	v_cvt_pk_bf16_f32 v110, v76, v77
	v_cvt_pk_bf16_f32 v111, v78, v79
	s_waitcnt lgkmcnt(7)
	v_mfma_f32_32x32x16_bf16 v[80:95], v[198:201], v[112:115], v[152:167]
	s_waitcnt lgkmcnt(6)
	v_mfma_f32_32x32x16_bf16 v[80:95], v[202:205], v[116:119], v[80:95]
	s_waitcnt lgkmcnt(5)
	v_mfma_f32_32x32x16_bf16 v[80:95], v[206:209], v[124:127], v[80:95]
	s_waitcnt lgkmcnt(4)
	v_mfma_f32_32x32x16_bf16 v[80:95], v[210:213], v[128:131], v[80:95]
	v_mfma_f32_32x32x16_bf16 v[64:79], v[198:201], v[132:135], v[168:183]
	v_mfma_f32_32x32x16_bf16 v[64:79], v[202:205], v[136:139], v[64:79]
	v_mfma_f32_32x32x16_bf16 v[64:79], v[206:209], v[140:143], v[64:79]
	v_mfma_f32_32x32x16_bf16 v[64:79], v[210:213], v[144:147], v[64:79]
	s_waitcnt lgkmcnt(3)
	v_mfma_f32_32x32x16_bf16 v[48:63], v[96:99], v[232:235], v[48:63]
	s_waitcnt lgkmcnt(2)
	v_mfma_f32_32x32x16_bf16 v[32:47], v[96:99], v[236:239], v[32:47]
	v_mfma_f32_32x32x16_bf16 v[16:31], v[104:107], v[232:235], v[16:31]
	v_mfma_f32_32x32x16_bf16 v[0:15], v[104:107], v[236:239], v[0:15]
	s_nop 1
	v_max3_f32 v252, v80, v81, v82
	v_max3_f32 v252, v252, v83, v84
	v_max3_f32 v252, v252, v85, v86
	v_max3_f32 v252, v252, v87, v88
	v_max3_f32 v252, v252, v89, v90
	v_max3_f32 v252, v252, v91, v92
	v_max3_f32 v252, v252, v93, v94
	v_max_f32_e32 v252, v252, v95
	s_waitcnt lgkmcnt(1)
	v_mfma_f32_32x32x16_bf16 v[48:63], v[100:103], v[240:243], v[48:63]
	s_waitcnt lgkmcnt(0)
	v_mfma_f32_32x32x16_bf16 v[32:47], v[100:103], v[244:247], v[32:47]
	v_mfma_f32_32x32x16_bf16 v[16:31], v[108:111], v[240:243], v[16:31]
	v_mfma_f32_32x32x16_bf16 v[0:15], v[108:111], v[244:247], v[0:15]
	ds_read_b128 v[232:235], v229 offset:8192
	ds_read_b128 v[236:239], v229 offset:12288
	ds_read_b128 v[240:243], v230 offset:8192
	ds_read_b128 v[244:247], v230 offset:12288
	s_waitcnt vmcnt(1)
	ds_write_b128 v224, v[120:123] offset:16384
	s_waitcnt vmcnt(0)
	ds_write_b64 v225, v[148:149] offset:24576
	ds_write_b64 v226, v[150:151] offset:24576
	s_cmp_ge_u32 s45, s41
	s_cbranch_scc1 .Lgq_nold2
	v_lshl_add_u64 v[248:249], v[194:195], 0, v[184:185]
	v_add_co_u32_e32 v248, vcc, 0x16091000, v248
	s_nop 1
	v_addc_co_u32_e32 v249, vcc, 0, v249, vcc
	global_load_dwordx4 v[120:123], v[248:249], off
	v_lshl_add_u64 v[248:249], v[196:197], 0, v[184:185]
	v_add_co_u32_e32 v248, vcc, 0x32800000, v248
	s_nop 1
	v_addc_co_u32_e32 v249, vcc, 0, v249, vcc
	global_load_dwordx4 v[148:151], v[248:249], off offset:256
.Lgq_nold2:
	v_max3_f32 v253, v64, v65, v66
	v_max3_f32 v253, v253, v67, v68
	v_max3_f32 v253, v253, v69, v70
	v_max3_f32 v253, v253, v71, v72
	v_max3_f32 v253, v253, v73, v74
	v_max3_f32 v253, v253, v75, v76
	v_max3_f32 v253, v253, v77, v78
	v_max_f32_e32 v253, v253, v79
	v_cmp_lt_f32_e32 vcc, s97, v252
	s_cbranch_vccnz .Lgq_rare4

.Lgq_back5:
	v_exp_f32_e32 v80, v80
	v_exp_f32_e32 v81, v81
	v_exp_f32_e32 v82, v82
	v_exp_f32_e32 v83, v83
	v_exp_f32_e32 v84, v84
	v_exp_f32_e32 v85, v85
	v_exp_f32_e32 v86, v86
	v_exp_f32_e32 v87, v87
	v_exp_f32_e32 v88, v88
	v_exp_f32_e32 v89, v89
	v_exp_f32_e32 v90, v90
	v_exp_f32_e32 v91, v91
	v_exp_f32_e32 v92, v92
	v_exp_f32_e32 v93, v93
	v_exp_f32_e32 v94, v94
	v_exp_f32_e32 v95, v95
	v_add_f32_e32 v206, v80, v81
	v_add_f32_e32 v207, v82, v83
	v_add_f32_e32 v208, v84, v85
	v_add_f32_e32 v209, v86, v87
	v_add_f32_e32 v210, v88, v89
	v_add_f32_e32 v211, v90, v91
	v_add_f32_e32 v212, v92, v93
	v_add_f32_e32 v213, v94, v95
	v_add_f32_e32 v206, v206, v207
	v_add_f32_e32 v208, v208, v209
	v_add_f32_e32 v210, v210, v211
	v_add_f32_e32 v212, v212, v213
	v_add_f32_e32 v206, v206, v208
	v_add_f32_e32 v210, v210, v212
	v_add_f32_e32 v206, v206, v210
	v_add_f32_e32 v250, v250, v206
	v_cvt_pk_bf16_f32 v198, v80, v81
	v_cvt_pk_bf16_f32 v199, v82, v83
	v_cvt_pk_bf16_f32 v200, v84, v85
	v_cvt_pk_bf16_f32 v201, v86, v87
	v_cvt_pk_bf16_f32 v202, v88, v89
	v_cvt_pk_bf16_f32 v203, v90, v91
	v_cvt_pk_bf16_f32 v204, v92, v93
	v_cvt_pk_bf16_f32 v205, v94, v95
	v_exp_f32_e32 v64, v64
	v_exp_f32_e32 v65, v65
	v_exp_f32_e32 v66, v66
	v_exp_f32_e32 v67, v67
	v_exp_f32_e32 v68, v68
	v_exp_f32_e32 v69, v69
	v_exp_f32_e32 v70, v70
	v_exp_f32_e32 v71, v71
	v_exp_f32_e32 v72, v72
	v_exp_f32_e32 v73, v73
	v_exp_f32_e32 v74, v74
	v_exp_f32_e32 v75, v75
	v_exp_f32_e32 v76, v76
	v_exp_f32_e32 v77, v77
	v_exp_f32_e32 v78, v78
	v_exp_f32_e32 v79, v79
	v_add_f32_e32 v206, v64, v65
	v_add_f32_e32 v207, v66, v67
	v_add_f32_e32 v208, v68, v69
	v_add_f32_e32 v209, v70, v71
	v_add_f32_e32 v210, v72, v73
	v_add_f32_e32 v211, v74, v75
	v_add_f32_e32 v212, v76, v77
	v_add_f32_e32 v213, v78, v79
	v_add_f32_e32 v206, v206, v207
	v_add_f32_e32 v208, v208, v209
	v_add_f32_e32 v210, v210, v211
	v_add_f32_e32 v212, v212, v213
	v_add_f32_e32 v206, v206, v208
	v_add_f32_e32 v210, v210, v212
	v_add_f32_e32 v206, v206, v210
	v_add_f32_e32 v251, v251, v206
	v_cvt_pk_bf16_f32 v206, v64, v65
	v_cvt_pk_bf16_f32 v207, v66, v67
	v_cvt_pk_bf16_f32 v208, v68, v69
	v_cvt_pk_bf16_f32 v209, v70, v71
	v_cvt_pk_bf16_f32 v210, v72, v73
	v_cvt_pk_bf16_f32 v211, v74, v75
	v_cvt_pk_bf16_f32 v212, v76, v77
	v_cvt_pk_bf16_f32 v213, v78, v79
	s_waitcnt lgkmcnt(6)
	v_mfma_f32_32x32x16_bf16 v[48:63], v[198:201], v[232:235], v[48:63]
	s_waitcnt lgkmcnt(5)
	v_mfma_f32_32x32x16_bf16 v[32:47], v[198:201], v[236:239], v[32:47]
	v_mfma_f32_32x32x16_bf16 v[16:31], v[206:209], v[232:235], v[16:31]
	v_mfma_f32_32x32x16_bf16 v[0:15], v[206:209], v[236:239], v[0:15]
	s_waitcnt lgkmcnt(4)
	v_mfma_f32_32x32x16_bf16 v[48:63], v[202:205], v[240:243], v[48:63]
	s_waitcnt lgkmcnt(3)
	v_mfma_f32_32x32x16_bf16 v[32:47], v[202:205], v[244:247], v[32:47]
	v_mfma_f32_32x32x16_bf16 v[16:31], v[210:213], v[240:243], v[16:31]
	v_mfma_f32_32x32x16_bf16 v[0:15], v[210:213], v[244:247], v[0:15]
	s_waitcnt lgkmcnt(0)
	s_barrier
	ds_read_b128 v[96:99], v227 offset:16384
	ds_read_b128 v[100:103], v228 offset:16384
	ds_read_b128 v[104:107], v229 offset:16384
	ds_read_b128 v[108:111], v230 offset:16384
	ds_read_b128 v[198:201], v227 offset:20480
	ds_read_b128 v[202:205], v228 offset:20480
	ds_read_b128 v[206:209], v229 offset:20480
	ds_read_b128 v[210:213], v230 offset:20480
	s_waitcnt lgkmcnt(7)
	v_mfma_f32_32x32x16_bf16 v[80:95], v[96:99], v[112:115], v[152:167]
	s_waitcnt lgkmcnt(6)
	v_mfma_f32_32x32x16_bf16 v[80:95], v[100:103], v[116:119], v[80:95]
	s_waitcnt lgkmcnt(5)
	v_mfma_f32_32x32x16_bf16 v[80:95], v[104:107], v[124:127], v[80:95]
	s_waitcnt lgkmcnt(4)
	v_mfma_f32_32x32x16_bf16 v[80:95], v[108:111], v[128:131], v[80:95]
	v_mfma_f32_32x32x16_bf16 v[64:79], v[96:99], v[132:135], v[168:183]
	v_mfma_f32_32x32x16_bf16 v[64:79], v[100:103], v[136:139], v[64:79]
	v_mfma_f32_32x32x16_bf16 v[64:79], v[104:107], v[140:143], v[64:79]
	v_mfma_f32_32x32x16_bf16 v[64:79], v[108:111], v[144:147], v[64:79]
	ds_read_b128 v[232:235], v227 offset:24576
	ds_read_b128 v[236:239], v227 offset:28672
	ds_read_b128 v[240:243], v228 offset:24576
	ds_read_b128 v[244:247], v228 offset:28672
	s_nop 3
	v_max3_f32 v252, v80, v81, v82
	v_max3_f32 v252, v252, v83, v84
	v_max3_f32 v252, v252, v85, v86
	v_max3_f32 v252, v252, v87, v88
	v_max3_f32 v252, v252, v89, v90
	v_max3_f32 v252, v252, v91, v92
	v_max3_f32 v252, v252, v93, v94
	v_max_f32_e32 v252, v252, v95
	v_max3_f32 v253, v64, v65, v66
	v_max3_f32 v253, v253, v67, v68
	v_max3_f32 v253, v253, v69, v70
	v_max3_f32 v253, v253, v71, v72
	v_max3_f32 v253, v253, v73, v74
	v_max3_f32 v253, v253, v75, v76
	v_max3_f32 v253, v253, v77, v78
	v_max_f32_e32 v253, v253, v79
	v_cmp_lt_f32_e32 vcc, s97, v252
	s_cbranch_vccnz .Lgq_rare8

.Lgq_back9:
	v_exp_f32_e32 v80, v80
	v_exp_f32_e32 v81, v81
	v_exp_f32_e32 v82, v82
	v_exp_f32_e32 v83, v83
	v_exp_f32_e32 v84, v84
	v_exp_f32_e32 v85, v85
	v_exp_f32_e32 v86, v86
	v_exp_f32_e32 v87, v87
	v_exp_f32_e32 v88, v88
	v_exp_f32_e32 v89, v89
	v_exp_f32_e32 v90, v90
	v_exp_f32_e32 v91, v91
	v_exp_f32_e32 v92, v92
	v_exp_f32_e32 v93, v93
	v_exp_f32_e32 v94, v94
	v_exp_f32_e32 v95, v95
	v_add_f32_e32 v104, v80, v81
	v_add_f32_e32 v105, v82, v83
	v_add_f32_e32 v106, v84, v85
	v_add_f32_e32 v107, v86, v87
	v_add_f32_e32 v108, v88, v89
	v_add_f32_e32 v109, v90, v91
	v_add_f32_e32 v110, v92, v93
	v_add_f32_e32 v111, v94, v95
	v_add_f32_e32 v104, v104, v105
	v_add_f32_e32 v106, v106, v107
	v_add_f32_e32 v108, v108, v109
	v_add_f32_e32 v110, v110, v111
	v_add_f32_e32 v104, v104, v106
	v_add_f32_e32 v108, v108, v110
	v_add_f32_e32 v104, v104, v108
	v_add_f32_e32 v250, v250, v104
	v_cvt_pk_bf16_f32 v96, v80, v81
	v_cvt_pk_bf16_f32 v97, v82, v83
	v_cvt_pk_bf16_f32 v98, v84, v85
	v_cvt_pk_bf16_f32 v99, v86, v87
	v_cvt_pk_bf16_f32 v100, v88, v89
	v_cvt_pk_bf16_f32 v101, v90, v91
	v_cvt_pk_bf16_f32 v102, v92, v93
	v_cvt_pk_bf16_f32 v103, v94, v95
	v_exp_f32_e32 v64, v64
	v_exp_f32_e32 v65, v65
	v_exp_f32_e32 v66, v66
	v_exp_f32_e32 v67, v67
	v_exp_f32_e32 v68, v68
	v_exp_f32_e32 v69, v69
	v_exp_f32_e32 v70, v70
	v_exp_f32_e32 v71, v71
	v_exp_f32_e32 v72, v72
	v_exp_f32_e32 v73, v73
	v_exp_f32_e32 v74, v74
	v_exp_f32_e32 v75, v75
	v_exp_f32_e32 v76, v76
	v_exp_f32_e32 v77, v77
	v_exp_f32_e32 v78, v78
	v_exp_f32_e32 v79, v79
	v_add_f32_e32 v104, v64, v65
	v_add_f32_e32 v105, v66, v67
	v_add_f32_e32 v106, v68, v69
	v_add_f32_e32 v107, v70, v71
	v_add_f32_e32 v108, v72, v73
	v_add_f32_e32 v109, v74, v75
	v_add_f32_e32 v110, v76, v77
	v_add_f32_e32 v111, v78, v79
	v_add_f32_e32 v104, v104, v105
	v_add_f32_e32 v106, v106, v107
	v_add_f32_e32 v108, v108, v109
	v_add_f32_e32 v110, v110, v111
	v_add_f32_e32 v104, v104, v106
	v_add_f32_e32 v108, v108, v110
	v_add_f32_e32 v104, v104, v108
	v_add_f32_e32 v251, v251, v104
	v_cvt_pk_bf16_f32 v104, v64, v65
	v_cvt_pk_bf16_f32 v105, v66, v67
	v_cvt_pk_bf16_f32 v106, v68, v69
	v_cvt_pk_bf16_f32 v107, v70, v71
	v_cvt_pk_bf16_f32 v108, v72, v73
	v_cvt_pk_bf16_f32 v109, v74, v75
	v_cvt_pk_bf16_f32 v110, v76, v77
	v_cvt_pk_bf16_f32 v111, v78, v79
	s_waitcnt lgkmcnt(7)
	v_mfma_f32_32x32x16_bf16 v[80:95], v[198:201], v[112:115], v[152:167]
	s_waitcnt lgkmcnt(6)
	v_mfma_f32_32x32x16_bf16 v[80:95], v[202:205], v[116:119], v[80:95]
	s_waitcnt lgkmcnt(5)
	v_mfma_f32_32x32x16_bf16 v[80:95], v[206:209], v[124:127], v[80:95]
	s_waitcnt lgkmcnt(4)
	v_mfma_f32_32x32x16_bf16 v[80:95], v[210:213], v[128:131], v[80:95]
	v_mfma_f32_32x32x16_bf16 v[64:79], v[198:201], v[132:135], v[168:183]
	v_mfma_f32_32x32x16_bf16 v[64:79], v[202:205], v[136:139], v[64:79]
	v_mfma_f32_32x32x16_bf16 v[64:79], v[206:209], v[140:143], v[64:79]
	v_mfma_f32_32x32x16_bf16 v[64:79], v[210:213], v[144:147], v[64:79]
	s_waitcnt lgkmcnt(3)
	v_mfma_f32_32x32x16_bf16 v[48:63], v[96:99], v[232:235], v[48:63]
	s_waitcnt lgkmcnt(2)
	v_mfma_f32_32x32x16_bf16 v[32:47], v[96:99], v[236:239], v[32:47]
	v_mfma_f32_32x32x16_bf16 v[16:31], v[104:107], v[232:235], v[16:31]
	v_mfma_f32_32x32x16_bf16 v[0:15], v[104:107], v[236:239], v[0:15]
	s_nop 1
	v_max3_f32 v252, v80, v81, v82
	v_max3_f32 v252, v252, v83, v84
	v_max3_f32 v252, v252, v85, v86
	v_max3_f32 v252, v252, v87, v88
	v_max3_f32 v252, v252, v89, v90
	v_max3_f32 v252, v252, v91, v92
	v_max3_f32 v252, v252, v93, v94
	v_max_f32_e32 v252, v252, v95
	s_waitcnt lgkmcnt(1)
	v_mfma_f32_32x32x16_bf16 v[48:63], v[100:103], v[240:243], v[48:63]
	s_waitcnt lgkmcnt(0)
	v_mfma_f32_32x32x16_bf16 v[32:47], v[100:103], v[244:247], v[32:47]
	v_mfma_f32_32x32x16_bf16 v[16:31], v[108:111], v[240:243], v[16:31]
	v_mfma_f32_32x32x16_bf16 v[0:15], v[108:111], v[244:247], v[0:15]
	ds_read_b128 v[232:235], v229 offset:24576
	ds_read_b128 v[236:239], v229 offset:28672
	ds_read_b128 v[240:243], v230 offset:24576
	ds_read_b128 v[244:247], v230 offset:28672
	s_waitcnt vmcnt(1)
	ds_write_b128 v224, v[120:123]
	s_waitcnt vmcnt(0)
	ds_write_b64 v225, v[148:149] offset:8192
	ds_write_b64 v226, v[150:151] offset:8192
	s_add_i32 s4, s45, 1
	s_cmp_ge_u32 s4, s41
	s_cbranch_scc1 .Lgq_nold11
	v_lshl_add_u64 v[248:249], v[194:195], 0, v[184:185]
	v_add_co_u32_e32 v248, vcc, 0x160d9000, v248
	s_nop 1
	v_addc_co_u32_e32 v249, vcc, 0, v249, vcc
	global_load_dwordx4 v[120:123], v[248:249], off
	v_lshl_add_u64 v[248:249], v[196:197], 0, v[184:185]
	v_add_co_u32_e32 v248, vcc, 0x32800000, v248
	s_nop 1
	v_addc_co_u32_e32 v249, vcc, 0, v249, vcc
	global_load_dwordx4 v[148:151], v[248:249], off offset:384

; __device__ __forceinline__ void attn_core_gqa2(LAS unsigned char* lds, const bf16* __restrict__ Qw, const bf16* __restrict__ Kg, const bf16* __restrict__ Vtg,
;                                                int N, f32x16 (&o)[2][2], const int wave_s) {
;     ...
;     for (int t = 0; t < NT; t += 2) { TILE2(0, t); TILE2(1, t + 1); }
.Lgq_back14:
	v_exp_f32_e32 v80, v80
	v_exp_f32_e32 v81, v81
	v_exp_f32_e32 v82, v82
	v_exp_f32_e32 v83, v83
	v_exp_f32_e32 v84, v84
	v_exp_f32_e32 v85, v85
	v_exp_f32_e32 v86, v86
	v_exp_f32_e32 v87, v87
	v_exp_f32_e32 v88, v88
	v_exp_f32_e32 v89, v89
	v_exp_f32_e32 v90, v90
	v_exp_f32_e32 v91, v91
	v_exp_f32_e32 v92, v92
	v_exp_f32_e32 v93, v93
	v_exp_f32_e32 v94, v94
	v_exp_f32_e32 v95, v95
	v_add_f32_e32 v206, v80, v81
	v_add_f32_e32 v207, v82, v83
	v_add_f32_e32 v208, v84, v85
	v_add_f32_e32 v209, v86, v87
	v_add_f32_e32 v210, v88, v89
	v_add_f32_e32 v211, v90, v91
	v_add_f32_e32 v212, v92, v93
	v_add_f32_e32 v213, v94, v95
	v_add_f32_e32 v206, v206, v207
	v_add_f32_e32 v208, v208, v209
	v_add_f32_e32 v210, v210, v211
	v_add_f32_e32 v212, v212, v213
	v_add_f32_e32 v206, v206, v208
	v_add_f32_e32 v210, v210, v212
	v_add_f32_e32 v206, v206, v210
	v_add_f32_e32 v250, v250, v206
	v_cvt_pk_bf16_f32 v198, v80, v81
	v_cvt_pk_bf16_f32 v199, v82, v83
	v_cvt_pk_bf16_f32 v200, v84, v85
	v_cvt_pk_bf16_f32 v201, v86, v87
	v_cvt_pk_bf16_f32 v202, v88, v89
	v_cvt_pk_bf16_f32 v203, v90, v91
	v_cvt_pk_bf16_f32 v204, v92, v93
	v_cvt_pk_bf16_f32 v205, v94, v95
	v_exp_f32_e32 v64, v64
	v_exp_f32_e32 v65, v65
	v_exp_f32_e32 v66, v66
	v_exp_f32_e32 v67, v67
	v_exp_f32_e32 v68, v68
	v_exp_f32_e32 v69, v69
	v_exp_f32_e32 v70, v70
	v_exp_f32_e32 v71, v71
	v_exp_f32_e32 v72, v72
	v_exp_f32_e32 v73, v73
	v_exp_f32_e32 v74, v74
	v_exp_f32_e32 v75, v75
	v_exp_f32_e32 v76, v76
	v_exp_f32_e32 v77, v77
	v_exp_f32_e32 v78, v78
	v_exp_f32_e32 v79, v79
	v_add_f32_e32 v206, v64, v65
	v_add_f32_e32 v207, v66, v67
	v_add_f32_e32 v208, v68, v69
	v_add_f32_e32 v209, v70, v71
	v_add_f32_e32 v210, v72, v73
	v_add_f32_e32 v211, v74, v75
	v_add_f32_e32 v212, v76, v77
	v_add_f32_e32 v213, v78, v79
	v_add_f32_e32 v206, v206, v207
	v_add_f32_e32 v208, v208, v209
	v_add_f32_e32 v210, v210, v211
	v_add_f32_e32 v212, v212, v213
	v_add_f32_e32 v206, v206, v208
	v_add_f32_e32 v210, v210, v212
	v_add_f32_e32 v206, v206, v210
	v_add_f32_e32 v251, v251, v206
	v_cvt_pk_bf16_f32 v206, v64, v65
	v_cvt_pk_bf16_f32 v207, v66, v67
	v_cvt_pk_bf16_f32 v208, v68, v69
	v_cvt_pk_bf16_f32 v209, v70, v71
	v_cvt_pk_bf16_f32 v210, v72, v73
	v_cvt_pk_bf16_f32 v211, v74, v75
	v_cvt_pk_bf16_f32 v212, v76, v77
	v_cvt_pk_bf16_f32 v213, v78, v79
	s_waitcnt lgkmcnt(6)
	v_mfma_f32_32x32x16_bf16 v[48:63], v[198:201], v[232:235], v[48:63]
	s_waitcnt lgkmcnt(5)
	v_mfma_f32_32x32x16_bf16 v[32:47], v[198:201], v[236:239], v[32:47]
	v_mfma_f32_32x32x16_bf16 v[16:31], v[206:209], v[232:235], v[16:31]
	v_mfma_f32_32x32x16_bf16 v[0:15], v[206:209], v[236:239], v[0:15]
	s_waitcnt lgkmcnt(4)
	v_mfma_f32_32x32x16_bf16 v[48:63], v[202:205], v[240:243], v[48:63]
	s_waitcnt lgkmcnt(3)
	v_mfma_f32_32x32x16_bf16 v[32:47], v[202:205], v[244:247], v[32:47]
	v_mfma_f32_32x32x16_bf16 v[16:31], v[210:213], v[240:243], v[16:31]
	v_mfma_f32_32x32x16_bf16 v[0:15], v[210:213], v[244:247], v[0:15]
	s_waitcnt lgkmcnt(0)
	s_barrier
	v_lshl_add_u64 v[194:195], v[194:195], 0, s[94:95]
	v_lshl_add_u64 v[196:197], v[196:197], 0, s[84:85]
	s_cmp_ge_u32 s45, s41
	s_cbranch_scc1 .Lgq_exit
	s_add_i32 s45, s45, 2
.Lgq_loop:
	ds_read_b128 v[96:99], v227
	ds_read_b128 v[100:103], v228
	ds_read_b128 v[104:107], v229
	ds_read_b128 v[108:111], v230
	ds_read_b128 v[198:201], v227 offset:4096
	ds_read_b128 v[202:205], v228 offset:4096
	ds_read_b128 v[206:209], v229 offset:4096
	ds_read_b128 v[210:213], v230 offset:4096
	s_waitcnt lgkmcnt(7)
	v_mfma_f32_32x32x16_bf16 v[80:95], v[96:99], v[112:115], v[152:167]
	s_waitcnt lgkmcnt(6)
	v_mfma_f32_32x32x16_bf16 v[80:95], v[100:103], v[116:119], v[80:95]
	s_waitcnt lgkmcnt(5)
	v_mfma_f32_32x32x16_bf16 v[80:95], v[104:107], v[124:127], v[80:95]
	s_waitcnt lgkmcnt(4)
	v_mfma_f32_32x32x16_bf16 v[80:95], v[108:111], v[128:131], v[80:95]
	v_mfma_f32_32x32x16_bf16 v[64:79], v[96:99], v[132:135], v[168:183]
	v_mfma_f32_32x32x16_bf16 v[64:79], v[100:103], v[136:139], v[64:79]
	v_mfma_f32_32x32x16_bf16 v[64:79], v[104:107], v[140:143], v[64:79]
	v_mfma_f32_32x32x16_bf16 v[64:79], v[108:111], v[144:147], v[64:79]
	ds_read_b128 v[232:235], v227 offset:8192
	ds_read_b128 v[236:239], v227 offset:12288
	ds_read_b128 v[240:243], v228 offset:8192
	ds_read_b128 v[244:247], v228 offset:12288
	s_nop 3
	v_max3_f32 v252, v80, v81, v82
	v_max3_f32 v252, v252, v83, v84
	v_max3_f32 v252, v252, v85, v86
	v_max3_f32 v252, v252, v87, v88
	v_max3_f32 v252, v252, v89, v90
	v_max3_f32 v252, v252, v91, v92
	v_max3_f32 v252, v252, v93, v94
	v_max_f32_e32 v252, v252, v95
	v_max3_f32 v253, v64, v65, v66
	v_max3_f32 v253, v253, v67, v68
	v_max3_f32 v253, v253, v69, v70
	v_max3_f32 v253, v253, v71, v72
	v_max3_f32 v253, v253, v73, v74
	v_max3_f32 v253, v253, v75, v76
	v_max3_f32 v253, v253, v77, v78
	v_max_f32_e32 v253, v253, v79
	v_cmp_lt_f32_e32 vcc, s97, v252
	s_cbranch_vccnz .Lgq_rare17

.Lgq_back18:
	v_exp_f32_e32 v80, v80
	v_exp_f32_e32 v81, v81
	v_exp_f32_e32 v82, v82
	v_exp_f32_e32 v83, v83
	v_exp_f32_e32 v84, v84
	v_exp_f32_e32 v85, v85
	v_exp_f32_e32 v86, v86
	v_exp_f32_e32 v87, v87
	v_exp_f32_e32 v88, v88
	v_exp_f32_e32 v89, v89
	v_exp_f32_e32 v90, v90
	v_exp_f32_e32 v91, v91
	v_exp_f32_e32 v92, v92
	v_exp_f32_e32 v93, v93
	v_exp_f32_e32 v94, v94
	v_exp_f32_e32 v95, v95
	v_add_f32_e32 v104, v80, v81
	v_add_f32_e32 v105, v82, v83
	v_add_f32_e32 v106, v84, v85
	v_add_f32_e32 v107, v86, v87
	v_add_f32_e32 v108, v88, v89
	v_add_f32_e32 v109, v90, v91
	v_add_f32_e32 v110, v92, v93
	v_add_f32_e32 v111, v94, v95
	v_add_f32_e32 v104, v104, v105
	v_add_f32_e32 v106, v106, v107
	v_add_f32_e32 v108, v108, v109
	v_add_f32_e32 v110, v110, v111
	v_add_f32_e32 v104, v104, v106
	v_add_f32_e32 v108, v108, v110
	v_add_f32_e32 v104, v104, v108
	v_add_f32_e32 v250, v250, v104
	v_cvt_pk_bf16_f32 v96, v80, v81
	v_cvt_pk_bf16_f32 v97, v82, v83
	v_cvt_pk_bf16_f32 v98, v84, v85
	v_cvt_pk_bf16_f32 v99, v86, v87
	v_cvt_pk_bf16_f32 v100, v88, v89
	v_cvt_pk_bf16_f32 v101, v90, v91
	v_cvt_pk_bf16_f32 v102, v92, v93
	v_cvt_pk_bf16_f32 v103, v94, v95
	v_exp_f32_e32 v64, v64
	v_exp_f32_e32 v65, v65
	v_exp_f32_e32 v66, v66
	v_exp_f32_e32 v67, v67
	v_exp_f32_e32 v68, v68
	v_exp_f32_e32 v69, v69
	v_exp_f32_e32 v70, v70
	v_exp_f32_e32 v71, v71
	v_exp_f32_e32 v72, v72
	v_exp_f32_e32 v73, v73
	v_exp_f32_e32 v74, v74
	v_exp_f32_e32 v75, v75
	v_exp_f32_e32 v76, v76
	v_exp_f32_e32 v77, v77
	v_exp_f32_e32 v78, v78
	v_exp_f32_e32 v79, v79
	v_add_f32_e32 v104, v64, v65
	v_add_f32_e32 v105, v66, v67
	v_add_f32_e32 v106, v68, v69
	v_add_f32_e32 v107, v70, v71
	v_add_f32_e32 v108, v72, v73
	v_add_f32_e32 v109, v74, v75
	v_add_f32_e32 v110, v76, v77
	v_add_f32_e32 v111, v78, v79
	v_add_f32_e32 v104, v104, v105
	v_add_f32_e32 v106, v106, v107
	v_add_f32_e32 v108, v108, v109
	v_add_f32_e32 v110, v110, v111
	v_add_f32_e32 v104, v104, v106
	v_add_f32_e32 v108, v108, v110
	v_add_f32_e32 v104, v104, v108
	v_add_f32_e32 v251, v251, v104
	v_cvt_pk_bf16_f32 v104, v64, v65
	v_cvt_pk_bf16_f32 v105, v66, v67
	v_cvt_pk_bf16_f32 v106, v68, v69
	v_cvt_pk_bf16_f32 v107, v70, v71
	v_cvt_pk_bf16_f32 v108, v72, v73
	v_cvt_pk_bf16_f32 v109, v74, v75
	v_cvt_pk_bf16_f32 v110, v76, v77
	v_cvt_pk_bf16_f32 v111, v78, v79
	s_waitcnt lgkmcnt(7)
	v_mfma_f32_32x32x16_bf16 v[80:95], v[198:201], v[112:115], v[152:167]
	s_waitcnt lgkmcnt(6)
	v_mfma_f32_32x32x16_bf16 v[80:95], v[202:205], v[116:119], v[80:95]
	s_waitcnt lgkmcnt(5)
	v_mfma_f32_32x32x16_bf16 v[80:95], v[206:209], v[124:127], v[80:95]
	s_waitcnt lgkmcnt(4)
	v_mfma_f32_32x32x16_bf16 v[80:95], v[210:213], v[128:131], v[80:95]
	v_mfma_f32_32x32x16_bf16 v[64:79], v[198:201], v[132:135], v[168:183]
	v_mfma_f32_32x32x16_bf16 v[64:79], v[202:205], v[136:139], v[64:79]
	v_mfma_f32_32x32x16_bf16 v[64:79], v[206:209], v[140:143], v[64:79]
	v_mfma_f32_32x32x16_bf16 v[64:79], v[210:213], v[144:147], v[64:79]
	s_waitcnt lgkmcnt(3)
	v_mfma_f32_32x32x16_bf16 v[48:63], v[96:99], v[232:235], v[48:63]
	s_waitcnt lgkmcnt(2)
	v_mfma_f32_32x32x16_bf16 v[32:47], v[96:99], v[236:239], v[32:47]
	v_mfma_f32_32x32x16_bf16 v[16:31], v[104:107], v[232:235], v[16:31]
	v_mfma_f32_32x32x16_bf16 v[0:15], v[104:107], v[236:239], v[0:15]
	s_nop 1
	v_max3_f32 v252, v80, v81, v82
	v_max3_f32 v252, v252, v83, v84
	v_max3_f32 v252, v252, v85, v86
	v_max3_f32 v252, v252, v87, v88
	v_max3_f32 v252, v252, v89, v90
	v_max3_f32 v252, v252, v91, v92
	v_max3_f32 v252, v252, v93, v94
	v_max_f32_e32 v252, v252, v95
	s_waitcnt lgkmcnt(1)
	v_mfma_f32_32x32x16_bf16 v[48:63], v[100:103], v[240:243], v[48:63]
	s_waitcnt lgkmcnt(0)
	v_mfma_f32_32x32x16_bf16 v[32:47], v[100:103], v[244:247], v[32:47]
	v_mfma_f32_32x32x16_bf16 v[16:31], v[108:111], v[240:243], v[16:31]
	v_mfma_f32_32x32x16_bf16 v[0:15], v[108:111], v[244:247], v[0:15]
	ds_read_b128 v[232:235], v229 offset:8192
	ds_read_b128 v[236:239], v229 offset:12288
	ds_read_b128 v[240:243], v230 offset:8192
	ds_read_b128 v[244:247], v230 offset:12288
	s_waitcnt vmcnt(1)
	ds_write_b128 v224, v[120:123] offset:16384
	s_waitcnt vmcnt(0)
	ds_write_b64 v225, v[148:149] offset:24576
	ds_write_b64 v226, v[150:151] offset:24576
	s_cmp_ge_u32 s45, s41
	s_cbranch_scc1 .Lgq_nold20
	v_lshl_add_u64 v[248:249], v[194:195], 0, v[184:185]
	v_add_co_u32_e32 v248, vcc, 0x16091000, v248
	s_nop 1
	v_addc_co_u32_e32 v249, vcc, 0, v249, vcc
	global_load_dwordx4 v[120:123], v[248:249], off
	v_lshl_add_u64 v[248:249], v[196:197], 0, v[184:185]
	v_add_co_u32_e32 v248, vcc, 0x32800000, v248
	s_nop 1
	v_addc_co_u32_e32 v249, vcc, 0, v249, vcc
	global_load_dwordx4 v[148:151], v[248:249], off offset:256

; __device__ __forceinline__ void attn_core_gqa2(LAS unsigned char* lds, const bf16* __restrict__ Qw, const bf16* __restrict__ Kg, const bf16* __restrict__ Vtg,
;                                                int N, f32x16 (&o)[2][2], const int wave_s) {
;     ...
;     for (int t = 0; t < NT; t += 2) { TILE2(0, t); TILE2(1, t + 1); }
.Lgq_back32:
	v_exp_f32_e32 v80, v80
	v_exp_f32_e32 v81, v81
	v_exp_f32_e32 v82, v82
	v_exp_f32_e32 v83, v83
	v_exp_f32_e32 v84, v84
	v_exp_f32_e32 v85, v85
	v_exp_f32_e32 v86, v86
	v_exp_f32_e32 v87, v87
	v_exp_f32_e32 v88, v88
	v_exp_f32_e32 v89, v89
	v_exp_f32_e32 v90, v90
	v_exp_f32_e32 v91, v91
	v_exp_f32_e32 v92, v92
	v_exp_f32_e32 v93, v93
	v_exp_f32_e32 v94, v94
	v_exp_f32_e32 v95, v95
	v_add_f32_e32 v206, v80, v81
	v_add_f32_e32 v207, v82, v83
	v_add_f32_e32 v208, v84, v85
	v_add_f32_e32 v209, v86, v87
	v_add_f32_e32 v210, v88, v89
	v_add_f32_e32 v211, v90, v91
	v_add_f32_e32 v212, v92, v93
	v_add_f32_e32 v213, v94, v95
	v_add_f32_e32 v206, v206, v207
	v_add_f32_e32 v208, v208, v209
	v_add_f32_e32 v210, v210, v211
	v_add_f32_e32 v212, v212, v213
	v_add_f32_e32 v206, v206, v208
	v_add_f32_e32 v210, v210, v212
	v_add_f32_e32 v206, v206, v210
	v_add_f32_e32 v250, v250, v206
	v_cvt_pk_bf16_f32 v198, v80, v81
	v_cvt_pk_bf16_f32 v199, v82, v83
	v_cvt_pk_bf16_f32 v200, v84, v85
	v_cvt_pk_bf16_f32 v201, v86, v87
	v_cvt_pk_bf16_f32 v202, v88, v89
	v_cvt_pk_bf16_f32 v203, v90, v91
	v_cvt_pk_bf16_f32 v204, v92, v93
	v_cvt_pk_bf16_f32 v205, v94, v95
	v_exp_f32_e32 v64, v64
	v_exp_f32_e32 v65, v65
	v_exp_f32_e32 v66, v66
	v_exp_f32_e32 v67, v67
	v_exp_f32_e32 v68, v68
	v_exp_f32_e32 v69, v69
	v_exp_f32_e32 v70, v70
	v_exp_f32_e32 v71, v71
	v_exp_f32_e32 v72, v72
	v_exp_f32_e32 v73, v73
	v_exp_f32_e32 v74, v74
	v_exp_f32_e32 v75, v75
	v_exp_f32_e32 v76, v76
	v_exp_f32_e32 v77, v77
	v_exp_f32_e32 v78, v78
	v_exp_f32_e32 v79, v79
	v_add_f32_e32 v206, v64, v65
	v_add_f32_e32 v207, v66, v67
	v_add_f32_e32 v208, v68, v69
	v_add_f32_e32 v209, v70, v71
	v_add_f32_e32 v210, v72, v73
	v_add_f32_e32 v211, v74, v75
	v_add_f32_e32 v212, v76, v77
	v_add_f32_e32 v213, v78, v79
	v_add_f32_e32 v206, v206, v207
	v_add_f32_e32 v208, v208, v209
	v_add_f32_e32 v210, v210, v211
	v_add_f32_e32 v212, v212, v213
	v_add_f32_e32 v206, v206, v208
	v_add_f32_e32 v210, v210, v212
	v_add_f32_e32 v206, v206, v210
	v_add_f32_e32 v251, v251, v206
	v_cvt_pk_bf16_f32 v206, v64, v65
	v_cvt_pk_bf16_f32 v207, v66, v67
	v_cvt_pk_bf16_f32 v208, v68, v69
	v_cvt_pk_bf16_f32 v209, v70, v71
	v_cvt_pk_bf16_f32 v210, v72, v73
	v_cvt_pk_bf16_f32 v211, v74, v75
	v_cvt_pk_bf16_f32 v212, v76, v77
	v_cvt_pk_bf16_f32 v213, v78, v79
	s_waitcnt lgkmcnt(6)
	v_mfma_f32_32x32x16_bf16 v[48:63], v[198:201], v[232:235], v[48:63]
	s_waitcnt lgkmcnt(5)
	v_mfma_f32_32x32x16_bf16 v[32:47], v[198:201], v[236:239], v[32:47]
	v_mfma_f32_32x32x16_bf16 v[16:31], v[206:209], v[232:235], v[16:31]
	v_mfma_f32_32x32x16_bf16 v[0:15], v[206:209], v[236:239], v[0:15]
	s_waitcnt lgkmcnt(4)
	v_mfma_f32_32x32x16_bf16 v[48:63], v[202:205], v[240:243], v[48:63]
	s_waitcnt lgkmcnt(3)
	v_mfma_f32_32x32x16_bf16 v[32:47], v[202:205], v[244:247], v[32:47]
	v_mfma_f32_32x32x16_bf16 v[16:31], v[210:213], v[240:243], v[16:31]
	v_mfma_f32_32x32x16_bf16 v[0:15], v[210:213], v[244:247], v[0:15]
	s_waitcnt lgkmcnt(0)
	s_barrier
	v_lshl_add_u64 v[194:195], v[194:195], 0, s[94:95]
	v_lshl_add_u64 v[196:197], v[196:197], 0, s[84:85]
	s_cmp_ge_u32 s45, s41
	s_cbranch_scc1 .Lgq_exit
	s_add_i32 s45, s45, 2
	s_branch .Lgq_loop
